# A, B and C attention loops hand-rescheduled (interleaved LDS reads under MFMAs, half-split softmax, C K-address immediates)
# speedup vs baseline: 1.0125x; 1.0125x over previous
; template <int DQK>
; __device__ __forceinline__ void qkt(f32x16& p0, f32x16& p1, const char* Ks, const bf16x8* qr, int r32, int hi) {
;   constexpr int KP = DQK * 2;
;   p0 = f32x16{}; p1 = f32x16{};
;   if constexpr (DQK == 64 && ATT_KPRELOAD) {
;     bf16x8 ka[4], kq[4];
; #pragma unroll
;     for (int d0 = 0; d0 < 4; ++d0) { const int cb = (d0 * 16 + hi * 8) * 2;
;       ka[d0] = *reinterpret_cast<const bf16x8*>(Ks + KSWZ(KP, r32, cb)); kq[d0] = *reinterpret_cast<const bf16x8*>(Ks + KSWZ(KP, 32 + r32, cb)); }
;     SBAR();
; #pragma unroll
;     for (int d0 = 0; d0 < 4; ++d0) { p0 = __builtin_amdgcn_mfma_f32_32x32x16_bf16(ka[d0], qr[d0], p0, 0, 0, 0); p1 = __builtin_amdgcn_mfma_f32_32x32x16_bf16(kq[d0], qr[d0], p1, 0, 0, 0); }
;     return;
;   }
; #pragma unroll
;   for (int d0 = 0; d0 < DQK / 16; ++d0) { const int cb = (d0 * 16 + hi * 8) * 2;
;     bf16x8 b0 = *reinterpret_cast<const bf16x8*>(Ks + KSWZ(KP, r32, cb));
;     bf16x8 b1 = *reinterpret_cast<const bf16x8*>(Ks + KSWZ(KP, 32 + r32, cb));
;     p0 = __builtin_amdgcn_mfma_f32_32x32x16_bf16(b0, qr[d0], p0, 0, 0, 0);
;     p1 = __builtin_amdgcn_mfma_f32_32x32x16_bf16(b1, qr[d0], p1, 0, 0, 0); }
; }
; __device__ __forceinline__ int v_st(int k, int c) { const int kk = k; return ((kk >> 3) * 4 + (c >> 5)) * 512 + ((kk & 7) * 32 + (c & 31)) * 2; }
; __device__ __forceinline__ int v_rd_base(int lane) { return ((lane & 3) << 3) | (((lane >> 2) & 3) << 6) | (((lane >> 4) & 1) << 5) | (((lane >> 5) & 1) << 8); }
; template <int OFF> __device__ __forceinline__ s16x4 tr_read(int vb) {
;   s16x4 r; asm volatile("ds_read_b64_tr_b16 %0, %1 offset:%2" : "=&v"(r) : "v"(vb), "i"(OFF) : "memory"); return r;
; }
; template <int D0> __device__ __forceinline__ void pv_one(f32x16& od, int vb, bf16x8 pa0, bf16x8 pa1, bf16x8 pa2, bf16x8 pa3) {
;   const s16x4 l0 = tr_read<v_rd_off(D0, 0, 0)>(vb), h0 = tr_read<v_rd_off(D0, 0, 1)>(vb), l1 = tr_read<v_rd_off(D0, 1, 0)>(vb), h1 = tr_read<v_rd_off(D0, 1, 1)>(vb);
;   const s16x4 l2 = tr_read<v_rd_off(D0, 2, 0)>(vb), h2 = tr_read<v_rd_off(D0, 2, 1)>(vb), l3 = tr_read<v_rd_off(D0, 3, 0)>(vb), h3 = tr_read<v_rd_off(D0, 3, 1)>(vb);
;   asm volatile("s_waitcnt lgkmcnt(0)" ::: "memory"); SBAR();
;     ...
;   od = __builtin_amdgcn_mfma_f32_32x32x16_bf16(pa0, PK(l0, h0), od, 0, 0, 0);
;   od = __builtin_amdgcn_mfma_f32_32x32x16_bf16(pa1, PK(l1, h1), od, 0, 0, 0);
.LBB0_578:
	s_and_b32 s6, s1, 1
	s_waitcnt lgkmcnt(0)
	s_barrier
	s_mul_i32 s7, s6, 0x6000
	s_add_i32 s7, s0, s7
	v_add3_u32 v218, s7, v224, v189
	v_add3_u32 v219, s7, v223, v189
	v_add3_u32 v220, s7, v222, v189
	v_add3_u32 v242, s7, v221, v189
	ds_read_b128 v[64:67], v218
	ds_read_b128 v[68:71], v219
	ds_read_b128 v[72:75], v220
	ds_read_b128 v[76:79], v242
	ds_read_b128 v[172:175], v218 offset:128
	ds_read_b128 v[176:179], v219 offset:128
	ds_read_b128 v[238:241], v220 offset:128
	ds_read_b128 v[214:217], v242 offset:128
	s_waitcnt lgkmcnt(7)
	v_mfma_f32_32x32x16_bf16 v[80:95], v[64:67], v[144:147], 0
	ds_read_b128 v[64:67], v218 offset:256
	s_waitcnt lgkmcnt(7)
	v_mfma_f32_32x32x16_bf16 v[80:95], v[68:71], v[140:143], v[80:95]
	ds_read_b128 v[68:71], v219 offset:256
	s_waitcnt lgkmcnt(7)
	v_mfma_f32_32x32x16_bf16 v[80:95], v[72:75], v[136:139], v[80:95]
	ds_read_b128 v[72:75], v220 offset:256
	s_waitcnt lgkmcnt(7)
	v_mfma_f32_32x32x16_bf16 v[80:95], v[76:79], v[132:135], v[80:95]
	ds_read_b128 v[76:79], v242 offset:256
	s_waitcnt lgkmcnt(7)
	v_mfma_f32_32x32x16_bf16 v[80:95], v[172:175], v[128:131], v[80:95]
	ds_read_b128 v[172:175], v218 offset:12288
	s_waitcnt lgkmcnt(7)
	v_mfma_f32_32x32x16_bf16 v[80:95], v[176:179], v[124:127], v[80:95]
	ds_read_b128 v[176:179], v219 offset:12288
	s_waitcnt lgkmcnt(7)
	v_mfma_f32_32x32x16_bf16 v[80:95], v[238:241], v[120:123], v[80:95]
	ds_read_b128 v[238:241], v220 offset:12288
	s_waitcnt lgkmcnt(7)
	v_mfma_f32_32x32x16_bf16 v[80:95], v[214:217], v[116:119], v[80:95]
	ds_read_b128 v[214:217], v242 offset:12288
	s_waitcnt lgkmcnt(7)
	v_mfma_f32_32x32x16_bf16 v[80:95], v[64:67], v[112:115], v[80:95]
	s_waitcnt lgkmcnt(6)
	v_mfma_f32_32x32x16_bf16 v[80:95], v[68:71], v[108:111], v[80:95]
	s_waitcnt lgkmcnt(5)
	v_mfma_f32_32x32x16_bf16 v[80:95], v[72:75], v[104:107], v[80:95]
	s_waitcnt lgkmcnt(4)
	v_mfma_f32_32x32x16_bf16 v[80:95], v[76:79], v[100:103], v[80:95]
	s_waitcnt lgkmcnt(3)
	v_mfma_f32_32x32x16_bf16 v[64:79], v[172:175], v[144:147], 0
	ds_read_b128 v[172:175], v218 offset:12416
	s_waitcnt lgkmcnt(3)
	v_mfma_f32_32x32x16_bf16 v[64:79], v[176:179], v[140:143], v[64:79]
	ds_read_b128 v[176:179], v219 offset:12416
	s_waitcnt lgkmcnt(3)
	v_mfma_f32_32x32x16_bf16 v[64:79], v[238:241], v[136:139], v[64:79]
	ds_read_b128 v[238:241], v220 offset:12416
	s_waitcnt lgkmcnt(3)
	v_mfma_f32_32x32x16_bf16 v[64:79], v[214:217], v[132:135], v[64:79]
	ds_read_b128 v[214:217], v242 offset:12416
	v_exp_f32_e32 v80, v80
	v_exp_f32_e32 v81, v81
	v_add_f32_e32 v191, 0, v80
	v_exp_f32_e32 v82, v82
	v_add_f32_e32 v191, v81, v191
	v_exp_f32_e32 v83, v83
	s_waitcnt lgkmcnt(3)
	v_mfma_f32_32x32x16_bf16 v[64:79], v[172:175], v[128:131], v[64:79]
	ds_read_b128 v[172:175], v218 offset:12544
	v_lshl_add_u32 v218, s6, 14, v187
	v_add_f32_e32 v191, v82, v191
	v_exp_f32_e32 v84, v84
	v_add_f32_e32 v191, v83, v191
	v_exp_f32_e32 v85, v85
	v_add_f32_e32 v191, v84, v191
	v_exp_f32_e32 v86, v86
	s_waitcnt lgkmcnt(3)
	v_mfma_f32_32x32x16_bf16 v[64:79], v[176:179], v[124:127], v[64:79]
	ds_read_b128 v[176:179], v219 offset:12544
	v_add_f32_e32 v191, v85, v191
	v_exp_f32_e32 v87, v87
	v_add_f32_e32 v191, v86, v191
	v_exp_f32_e32 v88, v88
	v_add_f32_e32 v191, v87, v191
	v_exp_f32_e32 v89, v89
	s_waitcnt lgkmcnt(3)
	v_mfma_f32_32x32x16_bf16 v[64:79], v[238:241], v[120:123], v[64:79]
	ds_read_b128 v[238:241], v220 offset:12544
	v_add_f32_e32 v191, v88, v191
	v_exp_f32_e32 v90, v90
	v_add_f32_e32 v191, v89, v191
	v_exp_f32_e32 v91, v91
	v_add_f32_e32 v191, v90, v191
	v_exp_f32_e32 v92, v92
	s_waitcnt lgkmcnt(3)
	v_mfma_f32_32x32x16_bf16 v[64:79], v[214:217], v[116:119], v[64:79]
	ds_read_b128 v[214:217], v242 offset:12544
	v_add_f32_e32 v191, v91, v191
	v_exp_f32_e32 v93, v93
	v_add_f32_e32 v191, v92, v191
	v_exp_f32_e32 v94, v94
	v_add_f32_e32 v191, v93, v191
	v_exp_f32_e32 v95, v95
	s_waitcnt lgkmcnt(3)
	v_mfma_f32_32x32x16_bf16 v[64:79], v[172:175], v[112:115], v[64:79]
	ds_read_b64_tr_b16 v[172:173], v218 offset:0x200
	ds_read_b64_tr_b16 v[174:175], v218 offset:0xa00
	v_add_f32_e32 v191, v94, v191
	s_nop 0
	v_add_f32_e32 v191, v95, v191
	v_cvt_pk_bf16_f32 v80, v80, v81
	v_cvt_pk_bf16_f32 v81, v82, v83
	v_cvt_pk_bf16_f32 v82, v84, v85
	s_waitcnt lgkmcnt(4)
	v_mfma_f32_32x32x16_bf16 v[64:79], v[176:179], v[108:111], v[64:79]
	ds_read_b64_tr_b16 v[176:177], v218 offset:0x1200
	ds_read_b64_tr_b16 v[178:179], v218 offset:0x1a00
	v_cvt_pk_bf16_f32 v83, v86, v87
	v_cvt_pk_bf16_f32 v84, v88, v89
	v_cvt_pk_bf16_f32 v85, v90, v91
	v_cvt_pk_bf16_f32 v86, v92, v93
	v_cvt_pk_bf16_f32 v87, v94, v95
	ds_read_b64_tr_b16 v[88:89], v218 offset:0x0
	ds_read_b64_tr_b16 v[90:91], v218 offset:0x800
	s_waitcnt lgkmcnt(7)
	v_mfma_f32_32x32x16_bf16 v[64:79], v[238:241], v[104:107], v[64:79]
	ds_read_b64_tr_b16 v[238:239], v218 offset:0x400
	ds_read_b64_tr_b16 v[240:241], v218 offset:0xc00
	ds_read_b64_tr_b16 v[92:93], v218 offset:0x1000
	ds_read_b64_tr_b16 v[94:95], v218 offset:0x1800
	s_waitcnt lgkmcnt(10)
	v_mfma_f32_32x32x16_bf16 v[64:79], v[214:217], v[100:103], v[64:79]
	ds_read_b64_tr_b16 v[214:215], v218 offset:0x1400
	ds_read_b64_tr_b16 v[216:217], v218 offset:0x1c00
	s_nop 1
	s_waitcnt lgkmcnt(6)
	v_mfma_f32_32x32x16_bf16 v[48:63], v[80:83], v[88:91], v[48:63]
	ds_read_b64_tr_b16 v[88:89], v218 offset:0x600
	ds_read_b64_tr_b16 v[90:91], v218 offset:0xe00
	v_exp_f32_e32 v64, v64
	v_exp_f32_e32 v65, v65
	v_add_f32_e32 v191, v64, v191
	s_waitcnt lgkmcnt(4)
; #define SBAR() __builtin_amdgcn_sched_barrier(0)
; template <bool FIXM>
; __device__ __forceinline__ void finishSM(f32x16& p0, f32x16& p1, float alpha, float& l_reg, bf16x8& pa0, bf16x8& pa1, bf16x8& pa2, bf16x8& pa3, const int kb, const int hi) {
;     ...
;   for (int r = 0; r < 16; ++r) p1[r] = __builtin_amdgcn_exp2f(p1[r]);
;   if constexpr (FIXM) { if (kb + KVBLK > LROWS) {
; #pragma unroll
;     for (int r = 0; r < 16; ++r) { if (kb + 32 + crow(r, hi) >= LROWS) p1[r] = 0.f; } } }
;   float ps = 0;
; #pragma unroll
;   for (int r = 0; r < 16; ++r) ps += p0[r];
; #pragma unroll
;   for (int r = 0; r < 16; ++r) ps += p1[r];
;   if constexpr (FIXM) l_reg += ps; else l_reg = l_reg * alpha + ps;
;     ...
;   PK4(p0, 0, pa0); PK4(p0, 8, pa1); PK4(p1, 0, pa2); PK4(p1, 8, pa3);
;     ...
; }
; template <int DQK>
; __device__ __forceinline__ void qkt(f32x16& p0, f32x16& p1, const char* Ks, const bf16x8* qr, int r32, int hi) {
;   constexpr int KP = DQK * 2;
;   p0 = f32x16{}; p1 = f32x16{};
;   if constexpr (DQK == 64 && ATT_KPRELOAD) {
;     bf16x8 ka[4], kq[4];
; #pragma unroll
;     for (int d0 = 0; d0 < 4; ++d0) { const int cb = (d0 * 16 + hi * 8) * 2;
;       ka[d0] = *reinterpret_cast<const bf16x8*>(Ks + KSWZ(KP, r32, cb)); kq[d0] = *reinterpret_cast<const bf16x8*>(Ks + KSWZ(KP, 32 + r32, cb)); }
;     SBAR();
; #pragma unroll
;     for (int d0 = 0; d0 < 4; ++d0) { p0 = __builtin_amdgcn_mfma_f32_32x32x16_bf16(ka[d0], qr[d0], p0, 0, 0, 0); p1 = __builtin_amdgcn_mfma_f32_32x32x16_bf16(kq[d0], qr[d0], p1, 0, 0, 0); }
;     return;
;   }
; #pragma unroll
;   for (int d0 = 0; d0 < DQK / 16; ++d0) { const int cb = (d0 * 16 + hi * 8) * 2;
;     bf16x8 b0 = *reinterpret_cast<const bf16x8*>(Ks + KSWZ(KP, r32, cb));
;     bf16x8 b1 = *reinterpret_cast<const bf16x8*>(Ks + KSWZ(KP, 32 + r32, cb));
;     p0 = __builtin_amdgcn_mfma_f32_32x32x16_bf16(b0, qr[d0], p0, 0, 0, 0);
;     p1 = __builtin_amdgcn_mfma_f32_32x32x16_bf16(b1, qr[d0], p1, 0, 0, 0); }
; }
; __device__ __forceinline__ int v_st(int k, int c) { const int kk = k; return ((kk >> 3) * 4 + (c >> 5)) * 512 + ((kk & 7) * 32 + (c & 31)) * 2; }
; __device__ __forceinline__ int v_rd_base(int lane) { return ((lane & 3) << 3) | (((lane >> 2) & 3) << 6) | (((lane >> 4) & 1) << 5) | (((lane >> 5) & 1) << 8); }
; template <int OFF> __device__ __forceinline__ s16x4 tr_read(int vb) {
	v_mfma_f32_32x32x16_bf16 v[48:63], v[84:87], v[92:95], v[48:63]
	ds_read_b64_tr_b16 v[92:93], v218 offset:0x1600
	ds_read_b64_tr_b16 v[94:95], v218 offset:0x1e00
	v_exp_f32_e32 v66, v66
	v_add_f32_e32 v191, v65, v191
	v_exp_f32_e32 v67, v67
	v_add_f32_e32 v191, v66, v191
	v_mfma_f32_32x32x16_bf16 v[32:47], v[80:83], v[172:175], v[32:47]
	ds_read_b64_tr_b16 v[172:173], v218 offset:0x2000
	ds_read_b64_tr_b16 v[174:175], v218 offset:0x2800
	v_exp_f32_e32 v68, v68
	v_add_f32_e32 v191, v67, v191
	v_exp_f32_e32 v69, v69
	v_add_f32_e32 v191, v68, v191
	v_mfma_f32_32x32x16_bf16 v[32:47], v[84:87], v[176:179], v[32:47]
	ds_read_b64_tr_b16 v[176:177], v218 offset:0x3000
	ds_read_b64_tr_b16 v[178:179], v218 offset:0x3800
	v_exp_f32_e32 v70, v70
	v_add_f32_e32 v191, v69, v191
	v_exp_f32_e32 v71, v71
	v_add_f32_e32 v191, v70, v191
	v_mfma_f32_32x32x16_bf16 v[16:31], v[80:83], v[238:241], v[16:31]
	ds_read_b64_tr_b16 v[238:239], v218 offset:0x2200
	ds_read_b64_tr_b16 v[240:241], v218 offset:0x2a00
	v_exp_f32_e32 v72, v72
	v_add_f32_e32 v191, v71, v191
	v_exp_f32_e32 v73, v73
	v_add_f32_e32 v191, v72, v191
	s_waitcnt lgkmcnt(10)
	v_mfma_f32_32x32x16_bf16 v[16:31], v[84:87], v[214:217], v[16:31]
	ds_read_b64_tr_b16 v[214:215], v218 offset:0x3200
	ds_read_b64_tr_b16 v[216:217], v218 offset:0x3a00
	v_exp_f32_e32 v74, v74
	v_add_f32_e32 v191, v73, v191
	v_exp_f32_e32 v75, v75
	v_add_f32_e32 v191, v74, v191
	s_waitcnt lgkmcnt(10)
	v_mfma_f32_32x32x16_bf16 v[0:15], v[80:83], v[88:91], v[0:15]
	ds_read_b64_tr_b16 v[88:89], v218 offset:0x2400
	ds_read_b64_tr_b16 v[90:91], v218 offset:0x2c00
	v_exp_f32_e32 v76, v76
	v_add_f32_e32 v191, v75, v191
	v_exp_f32_e32 v77, v77
	v_add_f32_e32 v191, v76, v191
	s_waitcnt lgkmcnt(10)
	v_mfma_f32_32x32x16_bf16 v[0:15], v[84:87], v[92:95], v[0:15]
	ds_read_b64_tr_b16 v[92:93], v218 offset:0x3400
	ds_read_b64_tr_b16 v[94:95], v218 offset:0x3c00
	v_exp_f32_e32 v78, v78
	v_add_f32_e32 v191, v77, v191
	v_exp_f32_e32 v79, v79
	v_add_f32_e32 v191, v78, v191
	s_nop 0
	v_add_f32_e32 v191, v79, v191
	v_cvt_pk_bf16_f32 v64, v64, v65
	v_cvt_pk_bf16_f32 v65, v66, v67
	v_cvt_pk_bf16_f32 v66, v68, v69
	v_cvt_pk_bf16_f32 v67, v70, v71
	v_cvt_pk_bf16_f32 v68, v72, v73
	v_cvt_pk_bf16_f32 v69, v74, v75
	v_cvt_pk_bf16_f32 v70, v76, v77
	v_cvt_pk_bf16_f32 v71, v78, v79
	v_add_f32_e32 v230, v230, v191
	s_nop 0
	s_waitcnt lgkmcnt(10)
	v_mfma_f32_32x32x16_bf16 v[48:63], v[64:67], v[172:175], v[48:63]
	ds_read_b64_tr_b16 v[172:173], v218 offset:0x2600
	ds_read_b64_tr_b16 v[174:175], v218 offset:0x2e00
	s_xor_b32 s7, s6, 1
	s_lshl_b32 s12, s7, 14
	s_mulk_i32 s7, 0x6000
	s_add_i32 s7, s0, s7
	v_add_u32_e32 v219, s12, v236
	s_waitcnt vmcnt(4)
	ds_write_b128 v219, v[152:155]
	s_waitcnt lgkmcnt(11)
	v_mfma_f32_32x32x16_bf16 v[48:63], v[68:71], v[176:179], v[48:63]
	ds_read_b64_tr_b16 v[176:177], v218 offset:0x3600
	ds_read_b64_tr_b16 v[178:179], v218 offset:0x3e00
	v_add_u32_e32 v219, s12, v237
	s_waitcnt vmcnt(3)
	ds_write_b128 v219, v[148:151]
	s_waitcnt lgkmcnt(12)
	v_mfma_f32_32x32x16_bf16 v[32:47], v[64:67], v[238:241], v[32:47]
	v_add_u32_e32 v219, s7, v225
	s_waitcnt vmcnt(2)
	ds_write_b128 v219, v[164:167]
	s_waitcnt lgkmcnt(11)
	v_mfma_f32_32x32x16_bf16 v[32:47], v[68:71], v[214:217], v[32:47]
	v_add_u32_e32 v219, s7, v226
	s_waitcnt vmcnt(1)
	ds_write_b128 v219, v[160:163]
	s_waitcnt lgkmcnt(10)
	v_mfma_f32_32x32x16_bf16 v[16:31], v[64:67], v[88:91], v[16:31]
	v_add_u32_e32 v219, s7, v227
	s_waitcnt vmcnt(0)
	ds_write_b128 v219, v[156:159]
	s_waitcnt lgkmcnt(9)
	v_mfma_f32_32x32x16_bf16 v[16:31], v[68:71], v[92:95], v[16:31]
	s_mov_b32 s38, s30
	s_mov_b32 s39, s31
	buffer_load_dwordx4 v[152:155], v228, s[28:31], s3 offen
	buffer_load_dwordx4 v[148:151], v229, s[28:31], s3 offen
	buffer_load_dwordx4 v[164:167], v186, s[36:39], s2 offen
	s_waitcnt lgkmcnt(7)
	v_mfma_f32_32x32x16_bf16 v[0:15], v[64:67], v[172:175], v[0:15]
	buffer_load_dwordx4 v[160:163], v188, s[36:39], s2 offen
	buffer_load_dwordx4 v[156:159], v190, s[36:39], s2 offen
	s_add_i32 s1, s1, 1
	s_add_i32 s2, s2, 0x18000
	s_add_i32 s3, s3, 0x20000
	s_cmp_eq_u32 s2, 0x1818000
	s_waitcnt lgkmcnt(4)
	v_mfma_f32_32x32x16_bf16 v[0:15], v[68:71], v[176:179], v[0:15]
	s_cbranch_scc0 .LBB0_578
	v_add_u32_e32 v220, 0x80, v224
	v_add_u32_e32 v219, 0x80, v223
	v_add_u32_e32 v218, 0x80, v222
	v_add_u32_e32 v217, 0x80, v221
	v_add_u32_e32 v216, 0x100, v224
	v_add_u32_e32 v215, 0x100, v223
	v_add_u32_e32 v214, 0x100, v222
	v_add_u32_e32 v191, 0x100, v221
	s_waitcnt lgkmcnt(0)
	s_barrier
; #define SBAR() __builtin_amdgcn_sched_barrier(0)
; template <int DQK>
; __device__ __forceinline__ void qkt(f32x16& p0, f32x16& p1, const char* Ks, const bf16x8* qr, int r32, int hi) {
;   constexpr int KP = DQK * 2;
;   p0 = f32x16{}; p1 = f32x16{};
;   if constexpr (DQK == 64 && ATT_KPRELOAD) {
;     bf16x8 ka[4], kq[4];
; #pragma unroll
;     for (int d0 = 0; d0 < 4; ++d0) { const int cb = (d0 * 16 + hi * 8) * 2;
;       ka[d0] = *reinterpret_cast<const bf16x8*>(Ks + KSWZ(KP, r32, cb)); kq[d0] = *reinterpret_cast<const bf16x8*>(Ks + KSWZ(KP, 32 + r32, cb)); }
;     SBAR();
; #pragma unroll
;     for (int d0 = 0; d0 < 4; ++d0) { p0 = __builtin_amdgcn_mfma_f32_32x32x16_bf16(ka[d0], qr[d0], p0, 0, 0, 0); p1 = __builtin_amdgcn_mfma_f32_32x32x16_bf16(kq[d0], qr[d0], p1, 0, 0, 0); }
;     return;
;   }
; #pragma unroll
;   for (int d0 = 0; d0 < DQK / 16; ++d0) { const int cb = (d0 * 16 + hi * 8) * 2;
;     bf16x8 b0 = *reinterpret_cast<const bf16x8*>(Ks + KSWZ(KP, r32, cb));
;     bf16x8 b1 = *reinterpret_cast<const bf16x8*>(Ks + KSWZ(KP, 32 + r32, cb));
;     p0 = __builtin_amdgcn_mfma_f32_32x32x16_bf16(b0, qr[d0], p0, 0, 0, 0);
;     p1 = __builtin_amdgcn_mfma_f32_32x32x16_bf16(b1, qr[d0], p1, 0, 0, 0); }
; }
; __device__ __forceinline__ int v_st(int k, int c) { const int kk = k; return ((kk >> 3) * 4 + (c >> 5)) * 512 + ((kk & 7) * 32 + (c & 31)) * 2; }
; __device__ __forceinline__ int v_rd_base(int lane) { return ((lane & 3) << 3) | (((lane >> 2) & 3) << 6) | (((lane >> 4) & 1) << 5) | (((lane >> 5) & 1) << 8); }
; template <int OFF> __device__ __forceinline__ s16x4 tr_read(int vb) {
;   s16x4 r; asm volatile("ds_read_b64_tr_b16 %0, %1 offset:%2" : "=&v"(r) : "v"(vb), "i"(OFF) : "memory"); return r;
; }
; template <int D0> __device__ __forceinline__ void pv_one(f32x16& od, int vb, bf16x8 pa0, bf16x8 pa1, bf16x8 pa2, bf16x8 pa3) {
;   const s16x4 l0 = tr_read<v_rd_off(D0, 0, 0)>(vb), h0 = tr_read<v_rd_off(D0, 0, 1)>(vb), l1 = tr_read<v_rd_off(D0, 1, 0)>(vb), h1 = tr_read<v_rd_off(D0, 1, 1)>(vb);
;   const s16x4 l2 = tr_read<v_rd_off(D0, 2, 0)>(vb), h2 = tr_read<v_rd_off(D0, 2, 1)>(vb), l3 = tr_read<v_rd_off(D0, 3, 0)>(vb), h3 = tr_read<v_rd_off(D0, 3, 1)>(vb);
;   asm volatile("s_waitcnt lgkmcnt(0)" ::: "memory"); SBAR();
	s_add_i32 s1, 0, 0x16000
	v_add3_u32 v68, s1, v224, v189
	ds_read_b128 v[64:67], v68
	v_add3_u32 v176, s1, v223, v189
	ds_read_b128 v[172:175], v176
	s_waitcnt lgkmcnt(1)
	v_mfma_f32_32x32x16_bf16 v[80:95], v[64:67], v[144:147], 0
	ds_read_b128 v[64:67], v68 offset:12288
	s_waitcnt lgkmcnt(1)
	v_mfma_f32_32x32x16_bf16 v[80:95], v[172:175], v[140:143], v[80:95]
	ds_read_b128 v[172:175], v176 offset:12288
	v_add3_u32 v176, s1, v222, v189
	s_waitcnt lgkmcnt(1)
	v_mfma_f32_32x32x16_bf16 v[64:79], v[64:67], v[144:147], 0
	s_waitcnt lgkmcnt(0)
	v_mfma_f32_32x32x16_bf16 v[64:79], v[172:175], v[140:143], v[64:79]
	ds_read_b128 v[172:175], v176
	s_waitcnt lgkmcnt(0)
	v_mfma_f32_32x32x16_bf16 v[80:95], v[172:175], v[136:139], v[80:95]
	ds_read_b128 v[172:175], v176 offset:12288
	v_add3_u32 v176, s1, v221, v189
	s_waitcnt lgkmcnt(0)
	v_mfma_f32_32x32x16_bf16 v[64:79], v[172:175], v[136:139], v[64:79]
	ds_read_b128 v[172:175], v176
	s_waitcnt lgkmcnt(0)
	v_mfma_f32_32x32x16_bf16 v[80:95], v[172:175], v[132:135], v[80:95]
	ds_read_b128 v[172:175], v176 offset:12288
	v_add3_u32 v176, s1, v220, v189
	s_waitcnt lgkmcnt(0)
	v_mfma_f32_32x32x16_bf16 v[64:79], v[172:175], v[132:135], v[64:79]
	ds_read_b128 v[172:175], v176
	s_waitcnt lgkmcnt(0)
	v_mfma_f32_32x32x16_bf16 v[80:95], v[172:175], v[128:131], v[80:95]
	ds_read_b128 v[172:175], v176 offset:12288
	v_add3_u32 v176, s1, v219, v189
	s_waitcnt lgkmcnt(0)
	v_mfma_f32_32x32x16_bf16 v[64:79], v[172:175], v[128:131], v[64:79]
	ds_read_b128 v[172:175], v176
	s_waitcnt lgkmcnt(0)
	v_mfma_f32_32x32x16_bf16 v[80:95], v[172:175], v[124:127], v[80:95]
	ds_read_b128 v[172:175], v176 offset:12288
	v_add3_u32 v176, s1, v218, v189
	s_waitcnt lgkmcnt(0)
	v_mfma_f32_32x32x16_bf16 v[64:79], v[172:175], v[124:127], v[64:79]
	ds_read_b128 v[172:175], v176
	s_waitcnt lgkmcnt(0)
	v_mfma_f32_32x32x16_bf16 v[80:95], v[172:175], v[120:123], v[80:95]
	ds_read_b128 v[172:175], v176 offset:12288
	v_add3_u32 v176, s1, v217, v189
	s_waitcnt lgkmcnt(0)
	v_mfma_f32_32x32x16_bf16 v[64:79], v[172:175], v[120:123], v[64:79]
	ds_read_b128 v[172:175], v176
	s_waitcnt lgkmcnt(0)
	v_mfma_f32_32x32x16_bf16 v[80:95], v[172:175], v[116:119], v[80:95]
	ds_read_b128 v[172:175], v176 offset:12288
	v_add3_u32 v176, s1, v216, v189
	s_waitcnt lgkmcnt(0)
	v_mfma_f32_32x32x16_bf16 v[64:79], v[172:175], v[116:119], v[64:79]
	ds_read_b128 v[172:175], v176
	s_waitcnt lgkmcnt(0)
	v_mfma_f32_32x32x16_bf16 v[80:95], v[172:175], v[112:115], v[80:95]
	ds_read_b128 v[172:175], v176 offset:12288
	v_add3_u32 v176, s1, v215, v189
	s_waitcnt lgkmcnt(0)
	v_mfma_f32_32x32x16_bf16 v[64:79], v[172:175], v[112:115], v[64:79]
	ds_read_b128 v[172:175], v176
	s_waitcnt lgkmcnt(0)
	v_mfma_f32_32x32x16_bf16 v[80:95], v[172:175], v[108:111], v[80:95]
	ds_read_b128 v[172:175], v176 offset:12288
	v_add3_u32 v176, s1, v214, v189
	s_waitcnt lgkmcnt(0)
	v_mfma_f32_32x32x16_bf16 v[64:79], v[172:175], v[108:111], v[64:79]
	ds_read_b128 v[172:175], v176
	s_waitcnt lgkmcnt(0)
	v_mfma_f32_32x32x16_bf16 v[80:95], v[172:175], v[104:107], v[80:95]
	ds_read_b128 v[172:175], v176 offset:12288
	v_add3_u32 v176, s1, v191, v189
	s_waitcnt lgkmcnt(0)
	v_mfma_f32_32x32x16_bf16 v[64:79], v[172:175], v[104:107], v[64:79]
	ds_read_b128 v[172:175], v176
	s_waitcnt lgkmcnt(0)
	v_mfma_f32_32x32x16_bf16 v[80:95], v[172:175], v[100:103], v[80:95]
	ds_read_b128 v[172:175], v176 offset:12288
	s_waitcnt lgkmcnt(0)
	v_mfma_f32_32x32x16_bf16 v[64:79], v[172:175], v[100:103], v[64:79]
	s_waitcnt vmcnt(4)
	ds_write_b128 v231, v[152:155]
	s_waitcnt vmcnt(3)
	ds_write_b128 v232, v[148:151]
	s_waitcnt vmcnt(2)
	ds_write_b128 v233, v[164:167]
	s_waitcnt vmcnt(1)
	ds_write_b128 v234, v[160:163]
	s_waitcnt vmcnt(0)
	ds_write_b128 v235, v[156:159]
	v_exp_f32_e32 v80, v80
	v_exp_f32_e32 v81, v81
	v_exp_f32_e32 v82, v82
	v_exp_f32_e32 v83, v83
	v_exp_f32_e32 v84, v84
	v_exp_f32_e32 v149, v64
	v_add_f32_e32 v64, 0, v80
	v_exp_f32_e32 v85, v85
	v_add_f32_e32 v64, v81, v64
	v_exp_f32_e32 v86, v86
	v_add_f32_e32 v64, v82, v64
	v_exp_f32_e32 v87, v87
	v_add_f32_e32 v64, v83, v64
	v_exp_f32_e32 v88, v88
	v_add_f32_e32 v64, v84, v64
	v_exp_f32_e32 v89, v89
	v_add_f32_e32 v64, v85, v64
	v_exp_f32_e32 v90, v90
	v_add_f32_e32 v64, v86, v64
	v_exp_f32_e32 v91, v91
	v_add_f32_e32 v64, v87, v64
	v_exp_f32_e32 v92, v92
	v_add_f32_e32 v64, v88, v64
	v_exp_f32_e32 v93, v93
	v_add_f32_e32 v64, v89, v64
	v_exp_f32_e32 v94, v94
	v_add_f32_e32 v64, v90, v64
	v_exp_f32_e32 v95, v95
	v_add_f32_e32 v64, v91, v64
	v_add_f32_e32 v64, v92, v64
	v_exp_f32_e32 v150, v65
	v_add_f32_e32 v64, v93, v64
	v_exp_f32_e32 v151, v66
	v_add_f32_e32 v64, v94, v64
	v_exp_f32_e32 v152, v67
	v_add_f32_e32 v64, v95, v64
	v_exp_f32_e32 v153, v68
	v_add_f32_e32 v64, v149, v64
	v_exp_f32_e32 v154, v69
	v_add_f32_e32 v64, v150, v64
	v_exp_f32_e32 v155, v70
	v_add_f32_e32 v64, v151, v64
	v_exp_f32_e32 v156, v71
	v_add_f32_e32 v64, v152, v64
	v_exp_f32_e32 v157, v72
	v_add_f32_e32 v64, v153, v64
	v_exp_f32_e32 v158, v73
	v_add_f32_e32 v64, v154, v64
	v_exp_f32_e32 v159, v74
	v_add_f32_e32 v64, v155, v64
	v_exp_f32_e32 v160, v75
	v_add_f32_e32 v64, v156, v64
	v_exp_f32_e32 v161, v76
	v_add_f32_e32 v64, v157, v64
	v_exp_f32_e32 v162, v77
	v_add_f32_e32 v64, v158, v64
	v_exp_f32_e32 v163, v78
	v_add_f32_e32 v64, v159, v64
	v_exp_f32_e32 v79, v79
	v_add_f32_e32 v64, v160, v64
	v_add_f32_e32 v64, v161, v64
	v_add_f32_e32 v64, v162, v64
	v_add_f32_e32 v64, v163, v64
	v_add_f32_e32 v64, v79, v64
	v_add_u32_e32 v148, 0x4000, v187
	v_add_f32_e32 v164, v230, v64
	v_cvt_pk_bf16_f32 v64, v80, v81
	v_cvt_pk_bf16_f32 v65, v82, v83
	v_cvt_pk_bf16_f32 v66, v84, v85
	v_cvt_pk_bf16_f32 v67, v86, v87
	v_cvt_pk_bf16_f32 v68, v88, v89
	v_cvt_pk_bf16_f32 v69, v90, v91
	v_cvt_pk_bf16_f32 v70, v92, v93
	v_cvt_pk_bf16_f32 v71, v94, v95
	v_cvt_pk_bf16_f32 v72, v149, v150
	v_cvt_pk_bf16_f32 v73, v151, v152
	v_cvt_pk_bf16_f32 v74, v153, v154
	v_cvt_pk_bf16_f32 v75, v155, v156
	v_cvt_pk_bf16_f32 v76, v157, v158
	v_cvt_pk_bf16_f32 v77, v159, v160
	v_cvt_pk_bf16_f32 v78, v161, v162
	v_cvt_pk_bf16_f32 v79, v163, v79
	ds_read_b64_tr_b16 v[80:81], v148 offset:0
	ds_read_b64_tr_b16 v[82:83], v148 offset:0x800
	ds_read_b64_tr_b16 v[84:85], v148 offset:0x1000
	ds_read_b64_tr_b16 v[86:87], v148 offset:0x1800
	ds_read_b64_tr_b16 v[88:89], v148 offset:0x2000
	ds_read_b64_tr_b16 v[90:91], v148 offset:0x2800
	ds_read_b64_tr_b16 v[92:93], v148 offset:0x3000
	ds_read_b64_tr_b16 v[94:95], v148 offset:0x3800
	s_waitcnt lgkmcnt(0)
; template <bool FIXM>
; __device__ __forceinline__ void partialSM(f32x16& p0, f32x16& p1, float& m_reg, float& mn, float& alpha, const float C, const float thrS, const int kb, const int hi) {
;   if constexpr (FIXM) {
; #pragma unroll
;     for (int r = 0; r < 16; ++r) p0[r] = __builtin_amdgcn_exp2f(p0[r]);
;     if (kb + KVBLK > LROWS) {
; #pragma unroll
;       for (int r = 0; r < 16; ++r) { if (kb + crow(r, hi) >= LROWS) p0[r] = 0.f; }
;     }
;     return;
;   }
;   if (kb + KVBLK > LROWS) {
; #pragma unroll
;     for (int r = 0; r < 16; ++r) { const int k0 = kb + crow(r, hi); if (k0 >= LROWS) p0[r] = -1e30f; if (k0 + 32 >= LROWS) p1[r] = -1e30f; }
;   }
;   float pmax = p0[0];
; #pragma unroll
;   for (int r = 1; r < 16; ++r) pmax = fmaxf(pmax, p0[r]);
; #pragma unroll
;   for (int r = 0; r < 16; ++r) pmax = fmaxf(pmax, p1[r]);
;   { auto rr = __builtin_amdgcn_permlane32_swap(__float_as_uint(pmax), __float_as_uint(pmax), false, false);
;     pmax = fmaxf(__uint_as_float(rr[0]), __uint_as_float(rr[1])); }
;   if (__builtin_expect(__all(pmax - m_reg <= thrS), 1)) { mn = m_reg; alpha = 1.f; }
;   else { mn = fmaxf(m_reg, pmax); alpha = __builtin_amdgcn_exp2f((m_reg - mn) * C); m_reg = mn; }
;   const float mnC = -mn * C;
; #pragma unroll
; template <int D0> __device__ __forceinline__ void pv_one(f32x16& od, int vb, bf16x8 pa0, bf16x8 pa1, bf16x8 pa2, bf16x8 pa3) {
;   const s16x4 l0 = tr_read<v_rd_off(D0, 0, 0)>(vb), h0 = tr_read<v_rd_off(D0, 0, 1)>(vb), l1 = tr_read<v_rd_off(D0, 1, 0)>(vb), h1 = tr_read<v_rd_off(D0, 1, 1)>(vb);
;   const s16x4 l2 = tr_read<v_rd_off(D0, 2, 0)>(vb), h2 = tr_read<v_rd_off(D0, 2, 1)>(vb), l3 = tr_read<v_rd_off(D0, 3, 0)>(vb), h3 = tr_read<v_rd_off(D0, 3, 1)>(vb);
;   asm volatile("s_waitcnt lgkmcnt(0)" ::: "memory"); SBAR();
;     ...
;   od = __builtin_amdgcn_mfma_f32_32x32x16_bf16(pa0, PK(l0, h0), od, 0, 0, 0);
;   od = __builtin_amdgcn_mfma_f32_32x32x16_bf16(pa1, PK(l1, h1), od, 0, 0, 0);
;   od = __builtin_amdgcn_mfma_f32_32x32x16_bf16(pa2, PK(l2, h2), od, 0, 0, 0);
;   od = __builtin_amdgcn_mfma_f32_32x32x16_bf16(pa3, PK(l3, h3), od, 0, 0, 0);
;     ...
; }
; __device__ __forceinline__ void pv_d0(f32x16* o, int vb, bf16x8 pa0, bf16x8 pa1, bf16x8 pa2, bf16x8 pa3) {
;   pv_one<0>(o[0], vb, pa0, pa1, pa2, pa3); pv_one<1>(o[1], vb, pa0, pa1, pa2, pa3); pv_one<2>(o[2], vb, pa0, pa1, pa2, pa3); pv_one<3>(o[3], vb, pa0, pa1, pa2, pa3);
	s_nop 0
	v_mfma_f32_32x32x16_bf16 v[48:63], v[64:67], v[80:83], v[48:63]
	ds_read_b64_tr_b16 v[80:81], v148 offset:0x200
	ds_read_b64_tr_b16 v[82:83], v148 offset:0xa00
	v_mfma_f32_32x32x16_bf16 v[48:63], v[68:71], v[84:87], v[48:63]
	ds_read_b64_tr_b16 v[84:85], v148 offset:0x1200
	ds_read_b64_tr_b16 v[86:87], v148 offset:0x1a00
	v_mfma_f32_32x32x16_bf16 v[48:63], v[72:75], v[88:91], v[48:63]
	ds_read_b64_tr_b16 v[88:89], v148 offset:0x2200
	ds_read_b64_tr_b16 v[90:91], v148 offset:0x2a00
	v_mfma_f32_32x32x16_bf16 v[48:63], v[76:79], v[92:95], v[48:63]
	ds_read_b64_tr_b16 v[92:93], v148 offset:0x3200
	ds_read_b64_tr_b16 v[94:95], v148 offset:0x3a00
	s_waitcnt lgkmcnt(0)
	v_mfma_f32_32x32x16_bf16 v[32:47], v[64:67], v[80:83], v[32:47]
	ds_read_b64_tr_b16 v[80:81], v148 offset:0x400
	ds_read_b64_tr_b16 v[82:83], v148 offset:0xc00
	v_mfma_f32_32x32x16_bf16 v[32:47], v[68:71], v[84:87], v[32:47]
	ds_read_b64_tr_b16 v[84:85], v148 offset:0x1400
	ds_read_b64_tr_b16 v[86:87], v148 offset:0x1c00
	v_mfma_f32_32x32x16_bf16 v[32:47], v[72:75], v[88:91], v[32:47]
	ds_read_b64_tr_b16 v[88:89], v148 offset:0x2400
	ds_read_b64_tr_b16 v[90:91], v148 offset:0x2c00
	v_mfma_f32_32x32x16_bf16 v[32:47], v[76:79], v[92:95], v[32:47]
	ds_read_b64_tr_b16 v[92:93], v148 offset:0x3400
	ds_read_b64_tr_b16 v[94:95], v148 offset:0x3c00
	s_waitcnt lgkmcnt(0)
	v_mfma_f32_32x32x16_bf16 v[16:31], v[64:67], v[80:83], v[16:31]
	ds_read_b64_tr_b16 v[80:81], v148 offset:0x600
	ds_read_b64_tr_b16 v[82:83], v148 offset:0xe00
	v_mfma_f32_32x32x16_bf16 v[16:31], v[68:71], v[84:87], v[16:31]
	ds_read_b64_tr_b16 v[84:85], v148 offset:0x1600
	ds_read_b64_tr_b16 v[86:87], v148 offset:0x1e00
	v_mfma_f32_32x32x16_bf16 v[16:31], v[72:75], v[88:91], v[16:31]
	ds_read_b64_tr_b16 v[88:89], v148 offset:0x2600
	ds_read_b64_tr_b16 v[90:91], v148 offset:0x2e00
	v_mfma_f32_32x32x16_bf16 v[16:31], v[76:79], v[92:95], v[16:31]
	ds_read_b64_tr_b16 v[92:93], v148 offset:0x3600
	ds_read_b64_tr_b16 v[94:95], v148 offset:0x3e00
	s_waitcnt lgkmcnt(0)
	v_mfma_f32_32x32x16_bf16 v[0:15], v[64:67], v[80:83], v[0:15]
	v_and_b32_e32 v148, 0x3fffffc0, v213
	s_waitcnt lgkmcnt(0)
	s_barrier
	v_mfma_f32_32x32x16_bf16 v[0:15], v[68:71], v[84:87], v[0:15]
	v_mfma_f32_32x32x16_bf16 v[0:15], v[72:75], v[88:91], v[0:15]
	v_mfma_f32_32x32x16_bf16 v[0:15], v[76:79], v[92:95], v[0:15]
	v_add3_u32 v64, s0, v224, v189
	ds_read_b128 v[64:67], v64
	v_add3_u32 v80, s0, v223, v189
	ds_read_b128 v[80:83], v80
	s_waitcnt lgkmcnt(1)
	v_mfma_f32_32x32x16_bf16 v[64:79], v[64:67], v[144:147], 0
	s_waitcnt lgkmcnt(0)
	v_mfma_f32_32x32x16_bf16 v[64:79], v[80:83], v[140:143], v[64:79]
	v_add3_u32 v80, s0, v222, v189
	ds_read_b128 v[80:83], v80
	s_waitcnt lgkmcnt(0)
	v_mfma_f32_32x32x16_bf16 v[64:79], v[80:83], v[136:139], v[64:79]
	v_add3_u32 v80, s0, v221, v189
	ds_read_b128 v[80:83], v80
	s_waitcnt lgkmcnt(0)
	v_mfma_f32_32x32x16_bf16 v[64:79], v[80:83], v[132:135], v[64:79]
	v_add3_u32 v80, s0, v220, v189
	ds_read_b128 v[80:83], v80
	s_waitcnt lgkmcnt(0)
	v_mfma_f32_32x32x16_bf16 v[64:79], v[80:83], v[128:131], v[64:79]
	v_add3_u32 v80, s0, v219, v189
	ds_read_b128 v[80:83], v80
	s_waitcnt lgkmcnt(0)
	v_mfma_f32_32x32x16_bf16 v[64:79], v[80:83], v[124:127], v[64:79]
	v_add3_u32 v80, s0, v218, v189
	ds_read_b128 v[80:83], v80
	s_waitcnt lgkmcnt(0)
	v_mfma_f32_32x32x16_bf16 v[64:79], v[80:83], v[120:123], v[64:79]
	v_add3_u32 v80, s0, v217, v189
	ds_read_b128 v[80:83], v80
	s_waitcnt lgkmcnt(0)
	v_mfma_f32_32x32x16_bf16 v[64:79], v[80:83], v[116:119], v[64:79]
	v_add3_u32 v80, s0, v216, v189
	ds_read_b128 v[80:83], v80
	s_waitcnt lgkmcnt(0)
	v_mfma_f32_32x32x16_bf16 v[64:79], v[80:83], v[112:115], v[64:79]
	v_add3_u32 v80, s0, v215, v189
	ds_read_b128 v[80:83], v80
	s_waitcnt lgkmcnt(0)
	v_mfma_f32_32x32x16_bf16 v[64:79], v[80:83], v[108:111], v[64:79]
	v_add3_u32 v80, s0, v214, v189
	ds_read_b128 v[80:83], v80
	s_waitcnt lgkmcnt(0)
	v_mfma_f32_32x32x16_bf16 v[64:79], v[80:83], v[104:107], v[64:79]
	v_add3_u32 v80, s0, v191, v189
	ds_read_b128 v[80:83], v80
	s_waitcnt lgkmcnt(0)
	v_mfma_f32_32x32x16_bf16 v[64:79], v[80:83], v[100:103], v[64:79]
	s_nop 11
	v_exp_f32_e32 v72, v64
	v_exp_f32_e32 v65, v65
	v_exp_f32_e32 v73, v66
	v_exp_f32_e32 v67, v67
	v_exp_f32_e32 v68, v68
	v_add_f32_e32 v64, 0, v72
	v_exp_f32_e32 v69, v69
	v_add_f32_e32 v64, v65, v64
	v_exp_f32_e32 v70, v70
	v_add_f32_e32 v64, v73, v64
	v_exp_f32_e32 v71, v71
	v_add_f32_e32 v64, v67, v64
	v_add_f32_e32 v64, v68, v64
	v_add_f32_e32 v64, v69, v64
	v_add_f32_e32 v64, v70, v64
	v_add_f32_e32 v64, v71, v64
	v_add_f32_e32 v64, 0, v64
	v_add_f32_e32 v64, v164, v64
	v_cvt_pk_bf16_f32 v66, v72, v65
	v_cvt_pk_bf16_f32 v67, v73, v67
	v_cvt_pk_bf16_f32 v68, v68, v69
	v_cvt_pk_bf16_f32 v69, v70, v71
	v_cvt_pk_bf16_f32 v70, v169, v169
	v_cvt_pk_bf16_f32 v71, v169, v169
	v_cvt_pk_bf16_f32 v72, v169, v169
	v_cvt_pk_bf16_f32 v73, v169, v169
	v_cvt_pk_bf16_f32 v74, v169, v169
	v_cvt_pk_bf16_f32 v75, v169, v169
	v_cvt_pk_bf16_f32 v76, v169, v169
	v_cvt_pk_bf16_f32 v77, v169, v169
	v_cvt_pk_bf16_f32 v78, v169, v169
	v_cvt_pk_bf16_f32 v79, v169, v169
	v_cvt_pk_bf16_f32 v80, v169, v169
	v_cvt_pk_bf16_f32 v81, v169, v169
	ds_read_b64_tr_b16 v[82:83], v187 offset:0
	ds_read_b64_tr_b16 v[84:85], v187 offset:0x800
	ds_read_b64_tr_b16 v[86:87], v187 offset:0x1000
	ds_read_b64_tr_b16 v[88:89], v187 offset:0x1800
	ds_read_b64_tr_b16 v[90:91], v187 offset:0x2000
	ds_read_b64_tr_b16 v[92:93], v187 offset:0x2800
	ds_read_b64_tr_b16 v[100:101], v187 offset:0x3000
	ds_read_b64_tr_b16 v[102:103], v187 offset:0x3800
	s_waitcnt lgkmcnt(0)
; #define SBAR() __builtin_amdgcn_sched_barrier(0)
; template <int D0> __device__ __forceinline__ void pv_one(f32x16& od, int vb, bf16x8 pa0, bf16x8 pa1, bf16x8 pa2, bf16x8 pa3) {
;   const s16x4 l0 = tr_read<v_rd_off(D0, 0, 0)>(vb), h0 = tr_read<v_rd_off(D0, 0, 1)>(vb), l1 = tr_read<v_rd_off(D0, 1, 0)>(vb), h1 = tr_read<v_rd_off(D0, 1, 1)>(vb);
;   const s16x4 l2 = tr_read<v_rd_off(D0, 2, 0)>(vb), h2 = tr_read<v_rd_off(D0, 2, 1)>(vb), l3 = tr_read<v_rd_off(D0, 3, 0)>(vb), h3 = tr_read<v_rd_off(D0, 3, 1)>(vb);
;   asm volatile("s_waitcnt lgkmcnt(0)" ::: "memory"); SBAR();
;     ...
;   od = __builtin_amdgcn_mfma_f32_32x32x16_bf16(pa0, PK(l0, h0), od, 0, 0, 0);
;   od = __builtin_amdgcn_mfma_f32_32x32x16_bf16(pa1, PK(l1, h1), od, 0, 0, 0);
;   od = __builtin_amdgcn_mfma_f32_32x32x16_bf16(pa2, PK(l2, h2), od, 0, 0, 0);
;   od = __builtin_amdgcn_mfma_f32_32x32x16_bf16(pa3, PK(l3, h3), od, 0, 0, 0);
;     ...
; }
; __device__ __forceinline__ void pv_d0(f32x16* o, int vb, bf16x8 pa0, bf16x8 pa1, bf16x8 pa2, bf16x8 pa3) {
;   pv_one<0>(o[0], vb, pa0, pa1, pa2, pa3); pv_one<1>(o[1], vb, pa0, pa1, pa2, pa3); pv_one<2>(o[2], vb, pa0, pa1, pa2, pa3); pv_one<3>(o[3], vb, pa0, pa1, pa2, pa3);
;     ...
;   { auto rr = __builtin_amdgcn_permlane32_swap(__float_as_uint(l_reg), __float_as_uint(l_reg), false, false);
;     l_reg = __uint_as_float(rr[0]) + __uint_as_float(rr[1]); }
;   if constexpr (SPLIT) if (part != nullptr) {
;     if (wid == 0) {
; #pragma unroll
;       for (int r = 0; r < 16; ++r) { const int orow = crow(r, hi);
;         if (orow < 16) {
; #pragma unroll
;           for (int d0 = 0; d0 < 4; ++d0) part[orow * 132 + d0 * 32 + r32] = o[d0][r]; } }
;       if (hi == 0 && r32 < 16) { part[r32 * 132 + 128] = m_reg; part[r32 * 132 + 129] = l_reg; }
;     }
;     __syncthreads();
;     return;
;   }
;   if (hi == 0) li_l[r32] = l_reg; asm volatile("s_waitcnt lgkmcnt(0)" ::: "memory");
; #pragma unroll
;   for (int r = 0; r < 16; ++r) { const int orow = wid * QBLK + crow(r, hi); const float rli = __builtin_amdgcn_rcpf(li_l[crow(r, hi)]);
;     if (orow < nvalid) {
;       if constexpr (MODE == 0) {
; #pragma unroll
;         for (int d0 = 0; d0 < 4; ++d0) Of[(long)orow * ldo + d0 * 32 + r32] = o[d0][r] * rli;
;       } else {
; #pragma unroll
;         for (int d0 = 0; d0 < 4; ++d0) { const float g = bf2f(Gb[(long)orow * ldg + d0 * 32 + r32]); const float sg = g / (1.f + __expf(-g));
	s_nop 0
	v_mfma_f32_32x32x16_bf16 v[48:63], v[66:69], v[82:85], v[48:63]
	ds_read_b64_tr_b16 v[82:83], v187 offset:0x200
	ds_read_b64_tr_b16 v[84:85], v187 offset:0xa00
	v_mfma_f32_32x32x16_bf16 v[48:63], v[70:73], v[86:89], v[48:63]
	ds_read_b64_tr_b16 v[86:87], v187 offset:0x1200
	ds_read_b64_tr_b16 v[88:89], v187 offset:0x1a00
	v_mfma_f32_32x32x16_bf16 v[48:63], v[74:77], v[90:93], v[48:63]
	ds_read_b64_tr_b16 v[90:91], v187 offset:0x2200
	ds_read_b64_tr_b16 v[92:93], v187 offset:0x2a00
	v_mfma_f32_32x32x16_bf16 v[48:63], v[78:81], v[100:103], v[48:63]
	ds_read_b64_tr_b16 v[100:101], v187 offset:0x3200
	ds_read_b64_tr_b16 v[102:103], v187 offset:0x3a00
	s_waitcnt lgkmcnt(0)
	v_mfma_f32_32x32x16_bf16 v[32:47], v[66:69], v[82:85], v[32:47]
	ds_read_b64_tr_b16 v[82:83], v187 offset:0x400
	ds_read_b64_tr_b16 v[84:85], v187 offset:0xc00
	v_mfma_f32_32x32x16_bf16 v[32:47], v[70:73], v[86:89], v[32:47]
	ds_read_b64_tr_b16 v[86:87], v187 offset:0x1400
	ds_read_b64_tr_b16 v[88:89], v187 offset:0x1c00
	v_mfma_f32_32x32x16_bf16 v[32:47], v[74:77], v[90:93], v[32:47]
	ds_read_b64_tr_b16 v[90:91], v187 offset:0x2400
	ds_read_b64_tr_b16 v[92:93], v187 offset:0x2c00
	v_mfma_f32_32x32x16_bf16 v[32:47], v[78:81], v[100:103], v[32:47]
	ds_read_b64_tr_b16 v[100:101], v187 offset:0x3400
	ds_read_b64_tr_b16 v[102:103], v187 offset:0x3c00
	s_waitcnt lgkmcnt(0)
	v_mfma_f32_32x32x16_bf16 v[16:31], v[66:69], v[82:85], v[16:31]
	ds_read_b64_tr_b16 v[82:83], v187 offset:0x600
	ds_read_b64_tr_b16 v[84:85], v187 offset:0xe00
	v_mfma_f32_32x32x16_bf16 v[16:31], v[70:73], v[86:89], v[16:31]
	ds_read_b64_tr_b16 v[86:87], v187 offset:0x1600
	ds_read_b64_tr_b16 v[88:89], v187 offset:0x1e00
	v_mfma_f32_32x32x16_bf16 v[16:31], v[74:77], v[90:93], v[16:31]
	ds_read_b64_tr_b16 v[90:91], v187 offset:0x2600
	ds_read_b64_tr_b16 v[92:93], v187 offset:0x2e00
	v_mfma_f32_32x32x16_bf16 v[16:31], v[78:81], v[100:103], v[16:31]
	ds_read_b64_tr_b16 v[100:101], v187 offset:0x3600
	ds_read_b64_tr_b16 v[102:103], v187 offset:0x3e00
	s_waitcnt lgkmcnt(0)
	v_mfma_f32_32x32x16_bf16 v[0:15], v[66:69], v[82:85], v[0:15]
	s_add_i32 s0, 0, 0x20000
	v_mov_b32_e32 v65, v64
	v_lshl_add_u32 v69, v148, 2, s0
	s_nop 0
	v_permlane32_swap_b32_e32 v64, v65
	v_cmp_gt_u32_e32 vcc, 32, v195
	v_mfma_f32_32x32x16_bf16 v[0:15], v[70:73], v[86:89], v[0:15]
	v_mfma_f32_32x32x16_bf16 v[0:15], v[74:77], v[90:93], v[0:15]
	v_mfma_f32_32x32x16_bf16 v[0:15], v[78:81], v[100:103], v[0:15]
	s_and_saveexec_b64 s[0:1], vcc
	v_lshl_add_u32 v66, v193, 2, v69
	v_add_f32_e32 v64, v64, v65
	ds_write_b32 v66, v64
	s_or_b64 exec, exec, s[0:1]
	s_lshl_b64 s[0:1], s[4:5], 12
	s_lshl_b32 s2, s97, 7
	s_mul_i32 s6, s4, 0x2e00
	s_mul_hi_u32 s3, s4, 0x2e00
	s_add_u32 s6, s10, s6
	s_addc_u32 s7, s11, s3
	v_readlane_b32 s18, v252, 49
	v_readlane_b32 s19, v252, 50
	s_add_u32 s12, s18, s0
	s_addc_u32 s18, s19, s1
	s_ashr_i32 s3, s2, 31
	s_lshl_b64 s[0:1], s[2:3], 1
	s_add_u32 s2, s12, s0
	s_addc_u32 s3, s18, s1
	s_add_u32 s0, s6, s0
	s_addc_u32 s1, s7, s1
	s_waitcnt lgkmcnt(0)
	v_lshlrev_b32_e32 v72, 2, v194
	v_lshlrev_b32_e32 v64, 1, v193
	v_mov_b32_e32 v65, v169
	v_lshl_add_u64 v[66:67], s[0:1], 0, v[64:65]
	s_mov_b64 s[0:1], 0x2180
	v_or_b32_e32 v68, v72, v192
	v_lshl_add_u64 v[66:67], v[66:67], 0, s[0:1]
	v_lshl_add_u64 v[64:65], s[2:3], 0, v[64:65]
	v_cmp_gt_i32_e32 vcc, s96, v68
	v_lshl_add_u32 v73, v72, 2, v69
	s_and_saveexec_b64 s[0:1], vcc
	s_cbranch_execz .LBB0_583
	v_mad_i64_i32 v[70:71], s[2:3], v68, s20, v[66:67]
	global_load_ushort v75, v[70:71], off
	ds_read_b32 v69, v73
	s_waitcnt lgkmcnt(0)
	v_rcp_f32_e32 v74, v69
	v_ashrrev_i32_e32 v69, 31, v68
	v_lshlrev_b64 v[68:69], 12, v[68:69]
	v_lshl_add_u64 v[68:69], v[64:65], 0, v[68:69]
	v_mul_f32_e32 v48, v48, v74
	v_mul_f32_e32 v32, v32, v74
	v_mul_f32_e32 v16, v16, v74
	v_mul_f32_e32 v0, v0, v74
	s_waitcnt vmcnt(0)
	v_lshlrev_b32_e32 v75, 16, v75
	v_mul_f32_e32 v76, 0xbfb8aa3b, v75
	v_exp_f32_e32 v76, v76
	s_nop 0
	v_add_f32_e32 v76, 1.0, v76
	v_div_scale_f32 v77, s[2:3], v76, v76, v75
	v_rcp_f32_e32 v78, v77
	s_nop 0
	v_fma_f32 v79, -v77, v78, 1.0
	v_fmac_f32_e32 v78, v79, v78
	v_div_scale_f32 v79, vcc, v75, v76, v75
	v_mul_f32_e32 v80, v79, v78
	v_fma_f32 v81, -v77, v80, v79
	v_fmac_f32_e32 v80, v81, v78
	v_fma_f32 v77, -v77, v80, v79
	v_div_fmas_f32 v77, v77, v78, v80
	v_div_fixup_f32 v75, v77, v76, v75
	v_mul_f32_e32 v48, v48, v75
	v_bfe_u32 v75, v48, 16, 1
	v_add3_u32 v48, v48, v75, s15
	global_store_short_d16_hi v[68:69], v48, off offset:2048
	global_load_ushort v48, v[70:71], off offset:64
	s_waitcnt vmcnt(0)
	v_lshlrev_b32_e32 v48, 16, v48
	v_mul_f32_e32 v75, 0xbfb8aa3b, v48
	v_exp_f32_e32 v75, v75
	s_nop 0
	v_add_f32_e32 v75, 1.0, v75
	v_div_scale_f32 v76, s[2:3], v75, v75, v48
	v_rcp_f32_e32 v77, v76
	s_nop 0
	v_fma_f32 v78, -v76, v77, 1.0
	v_fmac_f32_e32 v77, v78, v77
	v_div_scale_f32 v78, vcc, v48, v75, v48
	v_mul_f32_e32 v79, v78, v77
	v_fma_f32 v80, -v76, v79, v78
	v_fmac_f32_e32 v79, v80, v77
	v_fma_f32 v76, -v76, v79, v78
	v_div_fmas_f32 v76, v76, v77, v79
	v_div_fixup_f32 v48, v76, v75, v48
	v_mul_f32_e32 v32, v32, v48
	v_bfe_u32 v48, v32, 16, 1
	v_add3_u32 v32, v32, v48, s15
	global_store_short_d16_hi v[68:69], v32, off offset:2112
	global_load_ushort v32, v[70:71], off offset:128
	s_waitcnt vmcnt(0)
	v_lshlrev_b32_e32 v32, 16, v32
	v_mul_f32_e32 v48, 0xbfb8aa3b, v32
	v_exp_f32_e32 v48, v48
	s_nop 0
	v_add_f32_e32 v48, 1.0, v48
	v_div_scale_f32 v75, s[2:3], v48, v48, v32
	v_rcp_f32_e32 v76, v75
	s_nop 0
	v_fma_f32 v77, -v75, v76, 1.0
	v_fmac_f32_e32 v76, v77, v76
	v_div_scale_f32 v77, vcc, v32, v48, v32
	v_mul_f32_e32 v78, v77, v76
	v_fma_f32 v79, -v75, v78, v77
	v_fmac_f32_e32 v78, v79, v76
	v_fma_f32 v75, -v75, v78, v77
	v_div_fmas_f32 v75, v75, v76, v78
	v_div_fixup_f32 v32, v75, v48, v32
	v_mul_f32_e32 v16, v16, v32
	v_bfe_u32 v32, v16, 16, 1
	v_add3_u32 v16, v16, v32, s15
	global_store_short_d16_hi v[68:69], v16, off offset:2176
	global_load_ushort v16, v[70:71], off offset:192
	s_waitcnt vmcnt(0)
	v_lshlrev_b32_e32 v16, 16, v16
	v_mul_f32_e32 v32, 0xbfb8aa3b, v16
	v_exp_f32_e32 v32, v32
	s_nop 0
	v_add_f32_e32 v32, 1.0, v32
	v_div_scale_f32 v48, s[2:3], v32, v32, v16
	v_rcp_f32_e32 v70, v48
	s_nop 0
	v_fma_f32 v71, -v48, v70, 1.0
	v_fmac_f32_e32 v70, v71, v70
	v_div_scale_f32 v71, vcc, v16, v32, v16
	v_mul_f32_e32 v75, v71, v70
	v_fma_f32 v76, -v48, v75, v71
	v_fmac_f32_e32 v75, v76, v70
	v_fma_f32 v48, -v48, v75, v71
	v_div_fmas_f32 v48, v48, v70, v75
	v_div_fixup_f32 v16, v48, v32, v16
	v_mul_f32_e32 v0, v0, v16
	v_bfe_u32 v16, v0, 16, 1
	v_add3_u32 v0, v0, v16, s15
	global_store_short_d16_hi v[68:69], v0, off offset:2240
